# GDN: 16-lane reduce-scatter (8 masked DPP adds) + row_newbcast fmacs instead of 16-op all-reduce; LDS reads fill DPP wait states
# speedup vs baseline: 1.1722x; 1.0148x over previous
.Lgd2_loop:
	global_load_dword v108, v36, s[8:9]
	global_load_dword v109, v36, s[8:9] offset:-2048
	global_load_dword v111, v104, s[8:9] offset:2048
	global_load_dword v110, v37, s[10:11]
	global_load_dword v112, v105, s[10:11]
	global_load_dword v113, v106, s[12:13]
	s_add_u32 s8, s8, 0xc000
	s_addc_u32 s9, s9, 0
	s_add_u32 s10, s10, 0x20000
	s_addc_u32 s11, s11, 0
	s_add_u32 s12, s12, 0x400
	s_addc_u32 s13, s13, 0
	s_waitcnt lgkmcnt(0)
	v_pk_mul_f32 v[38:39], v[6:7], v[56:57] op_sel_hi:[1,0]
	v_pk_mul_f32 v[40:41], v[6:7], v[56:57] op_sel:[0,1] op_sel_hi:[1,1]
	v_pk_fma_f32 v[38:39], v[8:9], v[58:59], v[38:39] op_sel_hi:[1,0,1]
	v_pk_fma_f32 v[40:41], v[8:9], v[58:59], v[40:41] op_sel:[0,1,0] op_sel_hi:[1,1,1]
	v_pk_fma_f32 v[38:39], v[10:11], v[60:61], v[38:39] op_sel_hi:[1,0,1]
	v_pk_fma_f32 v[40:41], v[10:11], v[60:61], v[40:41] op_sel:[0,1,0] op_sel_hi:[1,1,1]
	v_pk_fma_f32 v[38:39], v[12:13], v[62:63], v[38:39] op_sel_hi:[1,0,1]
	v_pk_fma_f32 v[40:41], v[12:13], v[62:63], v[40:41] op_sel:[0,1,0] op_sel_hi:[1,1,1]
	v_pk_fma_f32 v[38:39], v[14:15], v[64:65], v[38:39] op_sel_hi:[1,0,1]
	v_pk_fma_f32 v[40:41], v[14:15], v[64:65], v[40:41] op_sel:[0,1,0] op_sel_hi:[1,1,1]
	v_pk_fma_f32 v[38:39], v[16:17], v[66:67], v[38:39] op_sel_hi:[1,0,1]
	v_pk_fma_f32 v[40:41], v[16:17], v[66:67], v[40:41] op_sel:[0,1,0] op_sel_hi:[1,1,1]
	v_pk_fma_f32 v[38:39], v[18:19], v[68:69], v[38:39] op_sel_hi:[1,0,1]
	v_pk_fma_f32 v[40:41], v[18:19], v[68:69], v[40:41] op_sel:[0,1,0] op_sel_hi:[1,1,1]
	v_pk_fma_f32 v[38:39], v[20:21], v[70:71], v[38:39] op_sel_hi:[1,0,1]
	v_pk_fma_f32 v[40:41], v[20:21], v[70:71], v[40:41] op_sel:[0,1,0] op_sel_hi:[1,1,1]
	v_mul_f32_e32 v50, v76, v51
	v_add_f32_dpp v38, v38, v38 row_ror:8 row_mask:0xf bank_mask:0x3 bound_ctrl:1
	v_add_f32_dpp v39, v39, v39 row_ror:8 row_mask:0xf bank_mask:0x3 bound_ctrl:1
	v_add_f32_dpp v38, v40, v40 row_ror:8 row_mask:0xf bank_mask:0xc bound_ctrl:1
	v_add_f32_dpp v39, v41, v41 row_ror:8 row_mask:0xf bank_mask:0xc bound_ctrl:1
	ds_read_b128 v[80:83], v22 offset:1024
	v_add_f32_dpp v38, v38, v38 row_half_mirror row_mask:0xf bank_mask:0x5 bound_ctrl:1
	v_add_f32_dpp v38, v39, v39 row_half_mirror row_mask:0xf bank_mask:0xa bound_ctrl:1
	ds_read_b128 v[84:87], v22 offset:1280
	ds_read_b128 v[88:91], v22 offset:1536
	v_add_f32_dpp v38, v38, v38 quad_perm:[1,0,3,2] row_mask:0xf bank_mask:0xf bound_ctrl:1
	ds_read_b128 v[92:95], v22 offset:1792
	ds_read_b64 v[96:97], v23 offset:12544
	v_add_f32_dpp v38, v38, v38 quad_perm:[2,3,0,1] row_mask:0xf bank_mask:0xf bound_ctrl:1
	ds_read_b128 v[100:103], v24 offset:14352
	v_cmp_gt_f32_e32 vcc, 0x2b8cbccc, v50
	v_fmac_f32_dpp v72, -v38, v50 row_newbcast:0 row_mask:0xf bank_mask:0xf bound_ctrl:1
	v_fmac_f32_dpp v73, -v38, v50 row_newbcast:4 row_mask:0xf bank_mask:0xf bound_ctrl:1
	v_pk_mul_f32 v[44:45], v[72:73], v[76:77] op_sel:[0,1] op_sel_hi:[1,1]
	v_pk_mul_f32 v[48:49], v[44:45], v[78:79] op_sel_hi:[1,0]
	v_rcp_f32_e32 v52, v50
	s_add_u32 s14, s14, 0x1000
	s_addc_u32 s15, s15, 0
	v_fmac_f32_dpp v48, v38, v50 row_newbcast:8 row_mask:0xf bank_mask:0xf bound_ctrl:1
	v_fmac_f32_dpp v49, v38, v50 row_newbcast:12 row_mask:0xf bank_mask:0xf bound_ctrl:1
	s_cbranch_vccnz .Lgd2_rare0
.Lgd2_back0:
	v_cvt_pk_bf16_f32 v54, v48, v49
	v_pk_mul_f32 v[46:47], v[44:45], v[52:53] op_sel_hi:[1,0]
	v_pk_fma_f32 v[6:7], v[56:57], v[46:47], v[6:7] op_sel_hi:[0,1,1]
	v_pk_fma_f32 v[8:9], v[58:59], v[46:47], v[8:9] op_sel_hi:[0,1,1]
	v_pk_fma_f32 v[10:11], v[60:61], v[46:47], v[10:11] op_sel_hi:[0,1,1]
	v_pk_fma_f32 v[12:13], v[62:63], v[46:47], v[12:13] op_sel_hi:[0,1,1]
	v_pk_fma_f32 v[14:15], v[64:65], v[46:47], v[14:15] op_sel_hi:[0,1,1]
	v_pk_fma_f32 v[16:17], v[66:67], v[46:47], v[16:17] op_sel_hi:[0,1,1]
	v_pk_fma_f32 v[18:19], v[68:69], v[46:47], v[18:19] op_sel_hi:[0,1,1]
	v_pk_fma_f32 v[20:21], v[70:71], v[46:47], v[20:21] op_sel_hi:[0,1,1]
	global_store_dword v154, v54, s[14:15] offset:-4096
	s_waitcnt lgkmcnt(0)
	v_pk_mul_f32 v[38:39], v[6:7], v[80:81] op_sel_hi:[1,0]
	v_pk_mul_f32 v[40:41], v[6:7], v[80:81] op_sel:[0,1] op_sel_hi:[1,1]
	v_pk_fma_f32 v[38:39], v[8:9], v[82:83], v[38:39] op_sel_hi:[1,0,1]
	v_pk_fma_f32 v[40:41], v[8:9], v[82:83], v[40:41] op_sel:[0,1,0] op_sel_hi:[1,1,1]
	v_pk_fma_f32 v[38:39], v[10:11], v[84:85], v[38:39] op_sel_hi:[1,0,1]
	v_pk_fma_f32 v[40:41], v[10:11], v[84:85], v[40:41] op_sel:[0,1,0] op_sel_hi:[1,1,1]
	v_pk_fma_f32 v[38:39], v[12:13], v[86:87], v[38:39] op_sel_hi:[1,0,1]
	v_pk_fma_f32 v[40:41], v[12:13], v[86:87], v[40:41] op_sel:[0,1,0] op_sel_hi:[1,1,1]
	v_pk_fma_f32 v[38:39], v[14:15], v[88:89], v[38:39] op_sel_hi:[1,0,1]
	v_pk_fma_f32 v[40:41], v[14:15], v[88:89], v[40:41] op_sel:[0,1,0] op_sel_hi:[1,1,1]
	v_pk_fma_f32 v[38:39], v[16:17], v[90:91], v[38:39] op_sel_hi:[1,0,1]
	v_pk_fma_f32 v[40:41], v[16:17], v[90:91], v[40:41] op_sel:[0,1,0] op_sel_hi:[1,1,1]
	v_pk_fma_f32 v[38:39], v[18:19], v[92:93], v[38:39] op_sel_hi:[1,0,1]
	v_pk_fma_f32 v[40:41], v[18:19], v[92:93], v[40:41] op_sel:[0,1,0] op_sel_hi:[1,1,1]
	v_pk_fma_f32 v[38:39], v[20:21], v[94:95], v[38:39] op_sel_hi:[1,0,1]
	v_pk_fma_f32 v[40:41], v[20:21], v[94:95], v[40:41] op_sel:[0,1,0] op_sel_hi:[1,1,1]
	v_mul_f32_e32 v51, v100, v50
	v_add_f32_dpp v38, v38, v38 row_ror:8 row_mask:0xf bank_mask:0x3 bound_ctrl:1
	v_add_f32_dpp v39, v39, v39 row_ror:8 row_mask:0xf bank_mask:0x3 bound_ctrl:1
	v_add_f32_dpp v38, v40, v40 row_ror:8 row_mask:0xf bank_mask:0xc bound_ctrl:1
	v_add_f32_dpp v39, v41, v41 row_ror:8 row_mask:0xf bank_mask:0xc bound_ctrl:1
	ds_read_b128 v[56:59], v22 offset:2048
	v_add_f32_dpp v38, v38, v38 row_half_mirror row_mask:0xf bank_mask:0x5 bound_ctrl:1
	v_add_f32_dpp v38, v39, v39 row_half_mirror row_mask:0xf bank_mask:0xa bound_ctrl:1
	ds_read_b128 v[60:63], v22 offset:2304
	ds_read_b128 v[64:67], v22 offset:2560
	v_add_f32_dpp v38, v38, v38 quad_perm:[1,0,3,2] row_mask:0xf bank_mask:0xf bound_ctrl:1
	ds_read_b128 v[68:71], v22 offset:2816
	ds_read_b64 v[72:73], v23 offset:12800
	v_add_f32_dpp v38, v38, v38 quad_perm:[2,3,0,1] row_mask:0xf bank_mask:0xf bound_ctrl:1
	ds_read_b128 v[76:79], v24 offset:14368
	v_cmp_gt_f32_e32 vcc, 0x2b8cbccc, v51
	v_fmac_f32_dpp v96, -v38, v51 row_newbcast:0 row_mask:0xf bank_mask:0xf bound_ctrl:1
	v_fmac_f32_dpp v97, -v38, v51 row_newbcast:4 row_mask:0xf bank_mask:0xf bound_ctrl:1
	v_pk_mul_f32 v[44:45], v[96:97], v[100:101] op_sel:[0,1] op_sel_hi:[1,1]
	v_pk_mul_f32 v[48:49], v[44:45], v[102:103] op_sel_hi:[1,0]
	v_rcp_f32_e32 v52, v51
	s_add_u32 s14, s14, 0x1000
	s_addc_u32 s15, s15, 0
	v_fmac_f32_dpp v48, v38, v51 row_newbcast:8 row_mask:0xf bank_mask:0xf bound_ctrl:1
	v_fmac_f32_dpp v49, v38, v51 row_newbcast:12 row_mask:0xf bank_mask:0xf bound_ctrl:1
	s_cbranch_vccnz .Lgd2_rare1
.Lgd2_back1:
	v_cvt_pk_bf16_f32 v54, v48, v49
	v_pk_mul_f32 v[46:47], v[44:45], v[52:53] op_sel_hi:[1,0]
	v_pk_fma_f32 v[6:7], v[80:81], v[46:47], v[6:7] op_sel_hi:[0,1,1]
	v_pk_fma_f32 v[8:9], v[82:83], v[46:47], v[8:9] op_sel_hi:[0,1,1]
	v_pk_fma_f32 v[10:11], v[84:85], v[46:47], v[10:11] op_sel_hi:[0,1,1]
	v_pk_fma_f32 v[12:13], v[86:87], v[46:47], v[12:13] op_sel_hi:[0,1,1]
	v_pk_fma_f32 v[14:15], v[88:89], v[46:47], v[14:15] op_sel_hi:[0,1,1]
	v_pk_fma_f32 v[16:17], v[90:91], v[46:47], v[16:17] op_sel_hi:[0,1,1]
	v_pk_fma_f32 v[18:19], v[92:93], v[46:47], v[18:19] op_sel_hi:[0,1,1]
	v_pk_fma_f32 v[20:21], v[94:95], v[46:47], v[20:21] op_sel_hi:[0,1,1]
	global_store_dword v154, v54, s[14:15] offset:-4096
	s_waitcnt lgkmcnt(0)
	v_pk_mul_f32 v[38:39], v[6:7], v[56:57] op_sel_hi:[1,0]
	v_pk_mul_f32 v[40:41], v[6:7], v[56:57] op_sel:[0,1] op_sel_hi:[1,1]
	v_pk_fma_f32 v[38:39], v[8:9], v[58:59], v[38:39] op_sel_hi:[1,0,1]
	v_pk_fma_f32 v[40:41], v[8:9], v[58:59], v[40:41] op_sel:[0,1,0] op_sel_hi:[1,1,1]
	v_pk_fma_f32 v[38:39], v[10:11], v[60:61], v[38:39] op_sel_hi:[1,0,1]
	v_pk_fma_f32 v[40:41], v[10:11], v[60:61], v[40:41] op_sel:[0,1,0] op_sel_hi:[1,1,1]
	v_pk_fma_f32 v[38:39], v[12:13], v[62:63], v[38:39] op_sel_hi:[1,0,1]
	v_pk_fma_f32 v[40:41], v[12:13], v[62:63], v[40:41] op_sel:[0,1,0] op_sel_hi:[1,1,1]
	v_pk_fma_f32 v[38:39], v[14:15], v[64:65], v[38:39] op_sel_hi:[1,0,1]
	v_pk_fma_f32 v[40:41], v[14:15], v[64:65], v[40:41] op_sel:[0,1,0] op_sel_hi:[1,1,1]
	v_pk_fma_f32 v[38:39], v[16:17], v[66:67], v[38:39] op_sel_hi:[1,0,1]
	v_pk_fma_f32 v[40:41], v[16:17], v[66:67], v[40:41] op_sel:[0,1,0] op_sel_hi:[1,1,1]
	v_pk_fma_f32 v[38:39], v[18:19], v[68:69], v[38:39] op_sel_hi:[1,0,1]
	v_pk_fma_f32 v[40:41], v[18:19], v[68:69], v[40:41] op_sel:[0,1,0] op_sel_hi:[1,1,1]
	v_pk_fma_f32 v[38:39], v[20:21], v[70:71], v[38:39] op_sel_hi:[1,0,1]
	v_pk_fma_f32 v[40:41], v[20:21], v[70:71], v[40:41] op_sel:[0,1,0] op_sel_hi:[1,1,1]
	v_mul_f32_e32 v50, v76, v51
	v_add_f32_dpp v38, v38, v38 row_ror:8 row_mask:0xf bank_mask:0x3 bound_ctrl:1
	v_add_f32_dpp v39, v39, v39 row_ror:8 row_mask:0xf bank_mask:0x3 bound_ctrl:1
	v_add_f32_dpp v38, v40, v40 row_ror:8 row_mask:0xf bank_mask:0xc bound_ctrl:1
	v_add_f32_dpp v39, v41, v41 row_ror:8 row_mask:0xf bank_mask:0xc bound_ctrl:1
	ds_read_b128 v[80:83], v22 offset:3072
	v_add_f32_dpp v38, v38, v38 row_half_mirror row_mask:0xf bank_mask:0x5 bound_ctrl:1
	v_add_f32_dpp v38, v39, v39 row_half_mirror row_mask:0xf bank_mask:0xa bound_ctrl:1
	ds_read_b128 v[84:87], v22 offset:3328
	ds_read_b128 v[88:91], v22 offset:3584
	v_add_f32_dpp v38, v38, v38 quad_perm:[1,0,3,2] row_mask:0xf bank_mask:0xf bound_ctrl:1
	ds_read_b128 v[92:95], v22 offset:3840
	ds_read_b64 v[96:97], v23 offset:13056
	v_add_f32_dpp v38, v38, v38 quad_perm:[2,3,0,1] row_mask:0xf bank_mask:0xf bound_ctrl:1
	ds_read_b128 v[100:103], v24 offset:14384
	v_cmp_gt_f32_e32 vcc, 0x2b8cbccc, v50
	v_fmac_f32_dpp v72, -v38, v50 row_newbcast:0 row_mask:0xf bank_mask:0xf bound_ctrl:1
	v_fmac_f32_dpp v73, -v38, v50 row_newbcast:4 row_mask:0xf bank_mask:0xf bound_ctrl:1
	v_pk_mul_f32 v[44:45], v[72:73], v[76:77] op_sel:[0,1] op_sel_hi:[1,1]
	v_pk_mul_f32 v[48:49], v[44:45], v[78:79] op_sel_hi:[1,0]
	v_rcp_f32_e32 v52, v50
	s_add_u32 s14, s14, 0x1000
	s_addc_u32 s15, s15, 0
	v_fmac_f32_dpp v48, v38, v50 row_newbcast:8 row_mask:0xf bank_mask:0xf bound_ctrl:1
	v_fmac_f32_dpp v49, v38, v50 row_newbcast:12 row_mask:0xf bank_mask:0xf bound_ctrl:1
	s_cbranch_vccnz .Lgd2_rare2
.Lgd2_back2:
	v_cvt_pk_bf16_f32 v54, v48, v49
	v_pk_mul_f32 v[46:47], v[44:45], v[52:53] op_sel_hi:[1,0]
	v_pk_fma_f32 v[6:7], v[56:57], v[46:47], v[6:7] op_sel_hi:[0,1,1]
	v_pk_fma_f32 v[8:9], v[58:59], v[46:47], v[8:9] op_sel_hi:[0,1,1]
	v_pk_fma_f32 v[10:11], v[60:61], v[46:47], v[10:11] op_sel_hi:[0,1,1]
	v_pk_fma_f32 v[12:13], v[62:63], v[46:47], v[12:13] op_sel_hi:[0,1,1]
	v_pk_fma_f32 v[14:15], v[64:65], v[46:47], v[14:15] op_sel_hi:[0,1,1]
	v_pk_fma_f32 v[16:17], v[66:67], v[46:47], v[16:17] op_sel_hi:[0,1,1]
	v_pk_fma_f32 v[18:19], v[68:69], v[46:47], v[18:19] op_sel_hi:[0,1,1]
	v_pk_fma_f32 v[20:21], v[70:71], v[46:47], v[20:21] op_sel_hi:[0,1,1]
	global_store_dword v154, v54, s[14:15] offset:-4096
	s_waitcnt lgkmcnt(0)
	v_pk_mul_f32 v[38:39], v[6:7], v[80:81] op_sel_hi:[1,0]
	v_pk_mul_f32 v[40:41], v[6:7], v[80:81] op_sel:[0,1] op_sel_hi:[1,1]
	v_pk_fma_f32 v[38:39], v[8:9], v[82:83], v[38:39] op_sel_hi:[1,0,1]
	v_pk_fma_f32 v[40:41], v[8:9], v[82:83], v[40:41] op_sel:[0,1,0] op_sel_hi:[1,1,1]
	v_pk_fma_f32 v[38:39], v[10:11], v[84:85], v[38:39] op_sel_hi:[1,0,1]
	v_pk_fma_f32 v[40:41], v[10:11], v[84:85], v[40:41] op_sel:[0,1,0] op_sel_hi:[1,1,1]
	v_pk_fma_f32 v[38:39], v[12:13], v[86:87], v[38:39] op_sel_hi:[1,0,1]
	v_pk_fma_f32 v[40:41], v[12:13], v[86:87], v[40:41] op_sel:[0,1,0] op_sel_hi:[1,1,1]
	v_pk_fma_f32 v[38:39], v[14:15], v[88:89], v[38:39] op_sel_hi:[1,0,1]
	v_pk_fma_f32 v[40:41], v[14:15], v[88:89], v[40:41] op_sel:[0,1,0] op_sel_hi:[1,1,1]
	v_pk_fma_f32 v[38:39], v[16:17], v[90:91], v[38:39] op_sel_hi:[1,0,1]
	v_pk_fma_f32 v[40:41], v[16:17], v[90:91], v[40:41] op_sel:[0,1,0] op_sel_hi:[1,1,1]
	v_pk_fma_f32 v[38:39], v[18:19], v[92:93], v[38:39] op_sel_hi:[1,0,1]
	v_pk_fma_f32 v[40:41], v[18:19], v[92:93], v[40:41] op_sel:[0,1,0] op_sel_hi:[1,1,1]
	v_pk_fma_f32 v[38:39], v[20:21], v[94:95], v[38:39] op_sel_hi:[1,0,1]
	v_pk_fma_f32 v[40:41], v[20:21], v[94:95], v[40:41] op_sel:[0,1,0] op_sel_hi:[1,1,1]
	v_mul_f32_e32 v51, v100, v50
	v_add_f32_dpp v38, v38, v38 row_ror:8 row_mask:0xf bank_mask:0x3 bound_ctrl:1
	v_add_f32_dpp v39, v39, v39 row_ror:8 row_mask:0xf bank_mask:0x3 bound_ctrl:1
	v_add_f32_dpp v38, v40, v40 row_ror:8 row_mask:0xf bank_mask:0xc bound_ctrl:1
	v_add_f32_dpp v39, v41, v41 row_ror:8 row_mask:0xf bank_mask:0xc bound_ctrl:1
	ds_read_b128 v[56:59], v22 offset:4096
	v_add_f32_dpp v38, v38, v38 row_half_mirror row_mask:0xf bank_mask:0x5 bound_ctrl:1
	v_add_f32_dpp v38, v39, v39 row_half_mirror row_mask:0xf bank_mask:0xa bound_ctrl:1
	ds_read_b128 v[60:63], v22 offset:4352
	ds_read_b128 v[64:67], v22 offset:4608
	v_add_f32_dpp v38, v38, v38 quad_perm:[1,0,3,2] row_mask:0xf bank_mask:0xf bound_ctrl:1
	ds_read_b128 v[68:71], v22 offset:4864
	ds_read_b64 v[72:73], v23 offset:13312
	v_add_f32_dpp v38, v38, v38 quad_perm:[2,3,0,1] row_mask:0xf bank_mask:0xf bound_ctrl:1
	ds_read_b128 v[76:79], v24 offset:14400
	v_cmp_gt_f32_e32 vcc, 0x2b8cbccc, v51
	v_fmac_f32_dpp v96, -v38, v51 row_newbcast:0 row_mask:0xf bank_mask:0xf bound_ctrl:1
	v_fmac_f32_dpp v97, -v38, v51 row_newbcast:4 row_mask:0xf bank_mask:0xf bound_ctrl:1
	v_pk_mul_f32 v[44:45], v[96:97], v[100:101] op_sel:[0,1] op_sel_hi:[1,1]
	v_pk_mul_f32 v[48:49], v[44:45], v[102:103] op_sel_hi:[1,0]
	v_rcp_f32_e32 v52, v51
	s_add_u32 s14, s14, 0x1000
	s_addc_u32 s15, s15, 0
	v_fmac_f32_dpp v48, v38, v51 row_newbcast:8 row_mask:0xf bank_mask:0xf bound_ctrl:1
	v_fmac_f32_dpp v49, v38, v51 row_newbcast:12 row_mask:0xf bank_mask:0xf bound_ctrl:1
	s_cbranch_vccnz .Lgd2_rare3
.Lgd2_back3:
	v_cvt_pk_bf16_f32 v54, v48, v49
	v_pk_mul_f32 v[46:47], v[44:45], v[52:53] op_sel_hi:[1,0]
	v_pk_fma_f32 v[6:7], v[80:81], v[46:47], v[6:7] op_sel_hi:[0,1,1]
	v_pk_fma_f32 v[8:9], v[82:83], v[46:47], v[8:9] op_sel_hi:[0,1,1]
	v_pk_fma_f32 v[10:11], v[84:85], v[46:47], v[10:11] op_sel_hi:[0,1,1]
	v_pk_fma_f32 v[12:13], v[86:87], v[46:47], v[12:13] op_sel_hi:[0,1,1]
	v_pk_fma_f32 v[14:15], v[88:89], v[46:47], v[14:15] op_sel_hi:[0,1,1]
	v_pk_fma_f32 v[16:17], v[90:91], v[46:47], v[16:17] op_sel_hi:[0,1,1]
	v_pk_fma_f32 v[18:19], v[92:93], v[46:47], v[18:19] op_sel_hi:[0,1,1]
	v_pk_fma_f32 v[20:21], v[94:95], v[46:47], v[20:21] op_sel_hi:[0,1,1]
	global_store_dword v154, v54, s[14:15] offset:-4096
	s_waitcnt lgkmcnt(0)
	v_pk_mul_f32 v[38:39], v[6:7], v[56:57] op_sel_hi:[1,0]
	v_pk_mul_f32 v[40:41], v[6:7], v[56:57] op_sel:[0,1] op_sel_hi:[1,1]
	v_pk_fma_f32 v[38:39], v[8:9], v[58:59], v[38:39] op_sel_hi:[1,0,1]
	v_pk_fma_f32 v[40:41], v[8:9], v[58:59], v[40:41] op_sel:[0,1,0] op_sel_hi:[1,1,1]
	v_pk_fma_f32 v[38:39], v[10:11], v[60:61], v[38:39] op_sel_hi:[1,0,1]
	v_pk_fma_f32 v[40:41], v[10:11], v[60:61], v[40:41] op_sel:[0,1,0] op_sel_hi:[1,1,1]
	v_pk_fma_f32 v[38:39], v[12:13], v[62:63], v[38:39] op_sel_hi:[1,0,1]
	v_pk_fma_f32 v[40:41], v[12:13], v[62:63], v[40:41] op_sel:[0,1,0] op_sel_hi:[1,1,1]
	v_pk_fma_f32 v[38:39], v[14:15], v[64:65], v[38:39] op_sel_hi:[1,0,1]
	v_pk_fma_f32 v[40:41], v[14:15], v[64:65], v[40:41] op_sel:[0,1,0] op_sel_hi:[1,1,1]
	v_pk_fma_f32 v[38:39], v[16:17], v[66:67], v[38:39] op_sel_hi:[1,0,1]
	v_pk_fma_f32 v[40:41], v[16:17], v[66:67], v[40:41] op_sel:[0,1,0] op_sel_hi:[1,1,1]
	v_pk_fma_f32 v[38:39], v[18:19], v[68:69], v[38:39] op_sel_hi:[1,0,1]
	v_pk_fma_f32 v[40:41], v[18:19], v[68:69], v[40:41] op_sel:[0,1,0] op_sel_hi:[1,1,1]
	v_pk_fma_f32 v[38:39], v[20:21], v[70:71], v[38:39] op_sel_hi:[1,0,1]
	v_pk_fma_f32 v[40:41], v[20:21], v[70:71], v[40:41] op_sel:[0,1,0] op_sel_hi:[1,1,1]
	v_mul_f32_e32 v50, v76, v51
	v_add_f32_dpp v38, v38, v38 row_ror:8 row_mask:0xf bank_mask:0x3 bound_ctrl:1
	v_add_f32_dpp v39, v39, v39 row_ror:8 row_mask:0xf bank_mask:0x3 bound_ctrl:1
	v_add_f32_dpp v38, v40, v40 row_ror:8 row_mask:0xf bank_mask:0xc bound_ctrl:1
	v_add_f32_dpp v39, v41, v41 row_ror:8 row_mask:0xf bank_mask:0xc bound_ctrl:1
	ds_read_b128 v[80:83], v22 offset:5120
	v_add_f32_dpp v38, v38, v38 row_half_mirror row_mask:0xf bank_mask:0x5 bound_ctrl:1
	v_add_f32_dpp v38, v39, v39 row_half_mirror row_mask:0xf bank_mask:0xa bound_ctrl:1
	ds_read_b128 v[84:87], v22 offset:5376
	ds_read_b128 v[88:91], v22 offset:5632
	v_add_f32_dpp v38, v38, v38 quad_perm:[1,0,3,2] row_mask:0xf bank_mask:0xf bound_ctrl:1
	ds_read_b128 v[92:95], v22 offset:5888
	ds_read_b64 v[96:97], v23 offset:13568
	v_add_f32_dpp v38, v38, v38 quad_perm:[2,3,0,1] row_mask:0xf bank_mask:0xf bound_ctrl:1
	ds_read_b128 v[100:103], v24 offset:14416
	v_cmp_gt_f32_e32 vcc, 0x2b8cbccc, v50
	v_fmac_f32_dpp v72, -v38, v50 row_newbcast:0 row_mask:0xf bank_mask:0xf bound_ctrl:1
	v_fmac_f32_dpp v73, -v38, v50 row_newbcast:4 row_mask:0xf bank_mask:0xf bound_ctrl:1
	v_pk_mul_f32 v[44:45], v[72:73], v[76:77] op_sel:[0,1] op_sel_hi:[1,1]
	v_pk_mul_f32 v[48:49], v[44:45], v[78:79] op_sel_hi:[1,0]
	v_rcp_f32_e32 v52, v50
	s_add_u32 s14, s14, 0x1000
	s_addc_u32 s15, s15, 0
	v_fmac_f32_dpp v48, v38, v50 row_newbcast:8 row_mask:0xf bank_mask:0xf bound_ctrl:1
	v_fmac_f32_dpp v49, v38, v50 row_newbcast:12 row_mask:0xf bank_mask:0xf bound_ctrl:1
	s_cbranch_vccnz .Lgd2_rare4
.Lgd2_back4:
	v_cvt_pk_bf16_f32 v54, v48, v49
	v_pk_mul_f32 v[46:47], v[44:45], v[52:53] op_sel_hi:[1,0]
	v_pk_fma_f32 v[6:7], v[56:57], v[46:47], v[6:7] op_sel_hi:[0,1,1]
	v_pk_fma_f32 v[8:9], v[58:59], v[46:47], v[8:9] op_sel_hi:[0,1,1]
	v_pk_fma_f32 v[10:11], v[60:61], v[46:47], v[10:11] op_sel_hi:[0,1,1]
	v_pk_fma_f32 v[12:13], v[62:63], v[46:47], v[12:13] op_sel_hi:[0,1,1]
	v_pk_fma_f32 v[14:15], v[64:65], v[46:47], v[14:15] op_sel_hi:[0,1,1]
	v_pk_fma_f32 v[16:17], v[66:67], v[46:47], v[16:17] op_sel_hi:[0,1,1]
	v_pk_fma_f32 v[18:19], v[68:69], v[46:47], v[18:19] op_sel_hi:[0,1,1]
	v_pk_fma_f32 v[20:21], v[70:71], v[46:47], v[20:21] op_sel_hi:[0,1,1]
	global_store_dword v154, v54, s[14:15] offset:-4096
	s_waitcnt lgkmcnt(0)
	v_pk_mul_f32 v[38:39], v[6:7], v[80:81] op_sel_hi:[1,0]
	v_pk_mul_f32 v[40:41], v[6:7], v[80:81] op_sel:[0,1] op_sel_hi:[1,1]
	v_pk_fma_f32 v[38:39], v[8:9], v[82:83], v[38:39] op_sel_hi:[1,0,1]
	v_pk_fma_f32 v[40:41], v[8:9], v[82:83], v[40:41] op_sel:[0,1,0] op_sel_hi:[1,1,1]
	v_pk_fma_f32 v[38:39], v[10:11], v[84:85], v[38:39] op_sel_hi:[1,0,1]
	v_pk_fma_f32 v[40:41], v[10:11], v[84:85], v[40:41] op_sel:[0,1,0] op_sel_hi:[1,1,1]
	v_pk_fma_f32 v[38:39], v[12:13], v[86:87], v[38:39] op_sel_hi:[1,0,1]
	v_pk_fma_f32 v[40:41], v[12:13], v[86:87], v[40:41] op_sel:[0,1,0] op_sel_hi:[1,1,1]
	v_pk_fma_f32 v[38:39], v[14:15], v[88:89], v[38:39] op_sel_hi:[1,0,1]
	v_pk_fma_f32 v[40:41], v[14:15], v[88:89], v[40:41] op_sel:[0,1,0] op_sel_hi:[1,1,1]
	v_pk_fma_f32 v[38:39], v[16:17], v[90:91], v[38:39] op_sel_hi:[1,0,1]
	v_pk_fma_f32 v[40:41], v[16:17], v[90:91], v[40:41] op_sel:[0,1,0] op_sel_hi:[1,1,1]
	v_pk_fma_f32 v[38:39], v[18:19], v[92:93], v[38:39] op_sel_hi:[1,0,1]
	v_pk_fma_f32 v[40:41], v[18:19], v[92:93], v[40:41] op_sel:[0,1,0] op_sel_hi:[1,1,1]
	v_pk_fma_f32 v[38:39], v[20:21], v[94:95], v[38:39] op_sel_hi:[1,0,1]
	v_pk_fma_f32 v[40:41], v[20:21], v[94:95], v[40:41] op_sel:[0,1,0] op_sel_hi:[1,1,1]
	v_mul_f32_e32 v51, v100, v50
	v_add_f32_dpp v38, v38, v38 row_ror:8 row_mask:0xf bank_mask:0x3 bound_ctrl:1
	v_add_f32_dpp v39, v39, v39 row_ror:8 row_mask:0xf bank_mask:0x3 bound_ctrl:1
	v_add_f32_dpp v38, v40, v40 row_ror:8 row_mask:0xf bank_mask:0xc bound_ctrl:1
	v_add_f32_dpp v39, v41, v41 row_ror:8 row_mask:0xf bank_mask:0xc bound_ctrl:1
	ds_read_b128 v[56:59], v22 offset:6144
	v_add_f32_dpp v38, v38, v38 row_half_mirror row_mask:0xf bank_mask:0x5 bound_ctrl:1
	v_add_f32_dpp v38, v39, v39 row_half_mirror row_mask:0xf bank_mask:0xa bound_ctrl:1
	ds_read_b128 v[60:63], v22 offset:6400
	ds_read_b128 v[64:67], v22 offset:6656
	v_add_f32_dpp v38, v38, v38 quad_perm:[1,0,3,2] row_mask:0xf bank_mask:0xf bound_ctrl:1
	ds_read_b128 v[68:71], v22 offset:6912
	ds_read_b64 v[72:73], v23 offset:13824
	v_add_f32_dpp v38, v38, v38 quad_perm:[2,3,0,1] row_mask:0xf bank_mask:0xf bound_ctrl:1
	ds_read_b128 v[76:79], v24 offset:14432
	v_cmp_gt_f32_e32 vcc, 0x2b8cbccc, v51
	v_fmac_f32_dpp v96, -v38, v51 row_newbcast:0 row_mask:0xf bank_mask:0xf bound_ctrl:1
	v_fmac_f32_dpp v97, -v38, v51 row_newbcast:4 row_mask:0xf bank_mask:0xf bound_ctrl:1
	v_pk_mul_f32 v[44:45], v[96:97], v[100:101] op_sel:[0,1] op_sel_hi:[1,1]
	v_pk_mul_f32 v[48:49], v[44:45], v[102:103] op_sel_hi:[1,0]
	v_rcp_f32_e32 v52, v51
	s_add_u32 s14, s14, 0x1000
	s_addc_u32 s15, s15, 0
	v_fmac_f32_dpp v48, v38, v51 row_newbcast:8 row_mask:0xf bank_mask:0xf bound_ctrl:1
	v_fmac_f32_dpp v49, v38, v51 row_newbcast:12 row_mask:0xf bank_mask:0xf bound_ctrl:1
	s_cbranch_vccnz .Lgd2_rare5
.Lgd2_back5:
	v_cvt_pk_bf16_f32 v54, v48, v49
	v_pk_mul_f32 v[46:47], v[44:45], v[52:53] op_sel_hi:[1,0]
	v_pk_fma_f32 v[6:7], v[80:81], v[46:47], v[6:7] op_sel_hi:[0,1,1]
	v_pk_fma_f32 v[8:9], v[82:83], v[46:47], v[8:9] op_sel_hi:[0,1,1]
	v_pk_fma_f32 v[10:11], v[84:85], v[46:47], v[10:11] op_sel_hi:[0,1,1]
	v_pk_fma_f32 v[12:13], v[86:87], v[46:47], v[12:13] op_sel_hi:[0,1,1]
	v_pk_fma_f32 v[14:15], v[88:89], v[46:47], v[14:15] op_sel_hi:[0,1,1]
	v_pk_fma_f32 v[16:17], v[90:91], v[46:47], v[16:17] op_sel_hi:[0,1,1]
	v_pk_fma_f32 v[18:19], v[92:93], v[46:47], v[18:19] op_sel_hi:[0,1,1]
	v_pk_fma_f32 v[20:21], v[94:95], v[46:47], v[20:21] op_sel_hi:[0,1,1]
	global_store_dword v154, v54, s[14:15] offset:-4096
	s_waitcnt lgkmcnt(0)
	v_pk_mul_f32 v[38:39], v[6:7], v[56:57] op_sel_hi:[1,0]
	v_pk_mul_f32 v[40:41], v[6:7], v[56:57] op_sel:[0,1] op_sel_hi:[1,1]
	v_pk_fma_f32 v[38:39], v[8:9], v[58:59], v[38:39] op_sel_hi:[1,0,1]
	v_pk_fma_f32 v[40:41], v[8:9], v[58:59], v[40:41] op_sel:[0,1,0] op_sel_hi:[1,1,1]
	v_pk_fma_f32 v[38:39], v[10:11], v[60:61], v[38:39] op_sel_hi:[1,0,1]
	v_pk_fma_f32 v[40:41], v[10:11], v[60:61], v[40:41] op_sel:[0,1,0] op_sel_hi:[1,1,1]
	v_pk_fma_f32 v[38:39], v[12:13], v[62:63], v[38:39] op_sel_hi:[1,0,1]
	v_pk_fma_f32 v[40:41], v[12:13], v[62:63], v[40:41] op_sel:[0,1,0] op_sel_hi:[1,1,1]
	v_pk_fma_f32 v[38:39], v[14:15], v[64:65], v[38:39] op_sel_hi:[1,0,1]
	v_pk_fma_f32 v[40:41], v[14:15], v[64:65], v[40:41] op_sel:[0,1,0] op_sel_hi:[1,1,1]
	v_pk_fma_f32 v[38:39], v[16:17], v[66:67], v[38:39] op_sel_hi:[1,0,1]
	v_pk_fma_f32 v[40:41], v[16:17], v[66:67], v[40:41] op_sel:[0,1,0] op_sel_hi:[1,1,1]
	v_pk_fma_f32 v[38:39], v[18:19], v[68:69], v[38:39] op_sel_hi:[1,0,1]
	v_pk_fma_f32 v[40:41], v[18:19], v[68:69], v[40:41] op_sel:[0,1,0] op_sel_hi:[1,1,1]
	v_pk_fma_f32 v[38:39], v[20:21], v[70:71], v[38:39] op_sel_hi:[1,0,1]
	v_pk_fma_f32 v[40:41], v[20:21], v[70:71], v[40:41] op_sel:[0,1,0] op_sel_hi:[1,1,1]
	v_mul_f32_e32 v50, v76, v51
	v_add_f32_dpp v38, v38, v38 row_ror:8 row_mask:0xf bank_mask:0x3 bound_ctrl:1
	v_add_f32_dpp v39, v39, v39 row_ror:8 row_mask:0xf bank_mask:0x3 bound_ctrl:1
	v_add_f32_dpp v38, v40, v40 row_ror:8 row_mask:0xf bank_mask:0xc bound_ctrl:1
	v_add_f32_dpp v39, v41, v41 row_ror:8 row_mask:0xf bank_mask:0xc bound_ctrl:1
	ds_read_b128 v[80:83], v22 offset:7168
	v_add_f32_dpp v38, v38, v38 row_half_mirror row_mask:0xf bank_mask:0x5 bound_ctrl:1
	v_add_f32_dpp v38, v39, v39 row_half_mirror row_mask:0xf bank_mask:0xa bound_ctrl:1
	ds_read_b128 v[84:87], v22 offset:7424
	ds_read_b128 v[88:91], v22 offset:7680
	v_add_f32_dpp v38, v38, v38 quad_perm:[1,0,3,2] row_mask:0xf bank_mask:0xf bound_ctrl:1
	ds_read_b128 v[92:95], v22 offset:7936
	ds_read_b64 v[96:97], v23 offset:14080
	v_add_f32_dpp v38, v38, v38 quad_perm:[2,3,0,1] row_mask:0xf bank_mask:0xf bound_ctrl:1
	ds_read_b128 v[100:103], v24 offset:14448
	v_cmp_gt_f32_e32 vcc, 0x2b8cbccc, v50
	v_fmac_f32_dpp v72, -v38, v50 row_newbcast:0 row_mask:0xf bank_mask:0xf bound_ctrl:1
	v_fmac_f32_dpp v73, -v38, v50 row_newbcast:4 row_mask:0xf bank_mask:0xf bound_ctrl:1
	v_pk_mul_f32 v[44:45], v[72:73], v[76:77] op_sel:[0,1] op_sel_hi:[1,1]
	v_pk_mul_f32 v[48:49], v[44:45], v[78:79] op_sel_hi:[1,0]
	v_rcp_f32_e32 v52, v50
	s_add_u32 s14, s14, 0x1000
	s_addc_u32 s15, s15, 0
	v_fmac_f32_dpp v48, v38, v50 row_newbcast:8 row_mask:0xf bank_mask:0xf bound_ctrl:1
	v_fmac_f32_dpp v49, v38, v50 row_newbcast:12 row_mask:0xf bank_mask:0xf bound_ctrl:1
	s_cbranch_vccnz .Lgd2_rare6
.Lgd2_back6:
	v_cvt_pk_bf16_f32 v54, v48, v49
	v_pk_mul_f32 v[46:47], v[44:45], v[52:53] op_sel_hi:[1,0]
	v_pk_fma_f32 v[6:7], v[56:57], v[46:47], v[6:7] op_sel_hi:[0,1,1]
	v_pk_fma_f32 v[8:9], v[58:59], v[46:47], v[8:9] op_sel_hi:[0,1,1]
	v_pk_fma_f32 v[10:11], v[60:61], v[46:47], v[10:11] op_sel_hi:[0,1,1]
	v_pk_fma_f32 v[12:13], v[62:63], v[46:47], v[12:13] op_sel_hi:[0,1,1]
	v_pk_fma_f32 v[14:15], v[64:65], v[46:47], v[14:15] op_sel_hi:[0,1,1]
	v_pk_fma_f32 v[16:17], v[66:67], v[46:47], v[16:17] op_sel_hi:[0,1,1]
	v_pk_fma_f32 v[18:19], v[68:69], v[46:47], v[18:19] op_sel_hi:[0,1,1]
	v_pk_fma_f32 v[20:21], v[70:71], v[46:47], v[20:21] op_sel_hi:[0,1,1]
	global_store_dword v154, v54, s[14:15] offset:-4096
	s_waitcnt lgkmcnt(0)
	v_pk_mul_f32 v[38:39], v[6:7], v[80:81] op_sel_hi:[1,0]
	v_pk_mul_f32 v[40:41], v[6:7], v[80:81] op_sel:[0,1] op_sel_hi:[1,1]
	v_pk_fma_f32 v[38:39], v[8:9], v[82:83], v[38:39] op_sel_hi:[1,0,1]
	v_pk_fma_f32 v[40:41], v[8:9], v[82:83], v[40:41] op_sel:[0,1,0] op_sel_hi:[1,1,1]
	v_pk_fma_f32 v[38:39], v[10:11], v[84:85], v[38:39] op_sel_hi:[1,0,1]
	v_pk_fma_f32 v[40:41], v[10:11], v[84:85], v[40:41] op_sel:[0,1,0] op_sel_hi:[1,1,1]
	v_pk_fma_f32 v[38:39], v[12:13], v[86:87], v[38:39] op_sel_hi:[1,0,1]
	v_pk_fma_f32 v[40:41], v[12:13], v[86:87], v[40:41] op_sel:[0,1,0] op_sel_hi:[1,1,1]
	v_pk_fma_f32 v[38:39], v[14:15], v[88:89], v[38:39] op_sel_hi:[1,0,1]
	v_pk_fma_f32 v[40:41], v[14:15], v[88:89], v[40:41] op_sel:[0,1,0] op_sel_hi:[1,1,1]
	v_pk_fma_f32 v[38:39], v[16:17], v[90:91], v[38:39] op_sel_hi:[1,0,1]
	v_pk_fma_f32 v[40:41], v[16:17], v[90:91], v[40:41] op_sel:[0,1,0] op_sel_hi:[1,1,1]
	v_pk_fma_f32 v[38:39], v[18:19], v[92:93], v[38:39] op_sel_hi:[1,0,1]
	v_pk_fma_f32 v[40:41], v[18:19], v[92:93], v[40:41] op_sel:[0,1,0] op_sel_hi:[1,1,1]
	v_pk_fma_f32 v[38:39], v[20:21], v[94:95], v[38:39] op_sel_hi:[1,0,1]
	v_pk_fma_f32 v[40:41], v[20:21], v[94:95], v[40:41] op_sel:[0,1,0] op_sel_hi:[1,1,1]
	v_mul_f32_e32 v51, v100, v50
	v_add_f32_dpp v38, v38, v38 row_ror:8 row_mask:0xf bank_mask:0x3 bound_ctrl:1
	v_add_f32_dpp v39, v39, v39 row_ror:8 row_mask:0xf bank_mask:0x3 bound_ctrl:1
	v_add_f32_dpp v38, v40, v40 row_ror:8 row_mask:0xf bank_mask:0xc bound_ctrl:1
	v_add_f32_dpp v39, v41, v41 row_ror:8 row_mask:0xf bank_mask:0xc bound_ctrl:1
	ds_read_b128 v[56:59], v25 offset:0
	v_add_f32_dpp v38, v38, v38 row_half_mirror row_mask:0xf bank_mask:0x5 bound_ctrl:1
	v_add_f32_dpp v38, v39, v39 row_half_mirror row_mask:0xf bank_mask:0xa bound_ctrl:1
	ds_read_b128 v[60:63], v25 offset:256
	ds_read_b128 v[64:67], v25 offset:512
	v_add_f32_dpp v38, v38, v38 quad_perm:[1,0,3,2] row_mask:0xf bank_mask:0xf bound_ctrl:1
	ds_read_b128 v[68:71], v25 offset:768
	ds_read_b64 v[72:73], v26 offset:12288
	v_add_f32_dpp v38, v38, v38 quad_perm:[2,3,0,1] row_mask:0xf bank_mask:0xf bound_ctrl:1
	ds_read_b128 v[76:79], v27 offset:14336
	v_cmp_gt_f32_e32 vcc, 0x2b8cbccc, v51
	v_fmac_f32_dpp v96, -v38, v51 row_newbcast:0 row_mask:0xf bank_mask:0xf bound_ctrl:1
	v_fmac_f32_dpp v97, -v38, v51 row_newbcast:4 row_mask:0xf bank_mask:0xf bound_ctrl:1
	v_pk_mul_f32 v[44:45], v[96:97], v[100:101] op_sel:[0,1] op_sel_hi:[1,1]
	v_pk_mul_f32 v[48:49], v[44:45], v[102:103] op_sel_hi:[1,0]
	v_rcp_f32_e32 v52, v51
	s_add_u32 s14, s14, 0x1000
	s_addc_u32 s15, s15, 0
	v_fmac_f32_dpp v48, v38, v51 row_newbcast:8 row_mask:0xf bank_mask:0xf bound_ctrl:1
	v_fmac_f32_dpp v49, v38, v51 row_newbcast:12 row_mask:0xf bank_mask:0xf bound_ctrl:1
	s_cbranch_vccnz .Lgd2_rare7
.Lgd2_back7:
	v_cvt_pk_bf16_f32 v54, v48, v49
	v_pk_mul_f32 v[46:47], v[44:45], v[52:53] op_sel_hi:[1,0]
	v_pk_fma_f32 v[6:7], v[80:81], v[46:47], v[6:7] op_sel_hi:[0,1,1]
	v_pk_fma_f32 v[8:9], v[82:83], v[46:47], v[8:9] op_sel_hi:[0,1,1]
	v_pk_fma_f32 v[10:11], v[84:85], v[46:47], v[10:11] op_sel_hi:[0,1,1]
	v_pk_fma_f32 v[12:13], v[86:87], v[46:47], v[12:13] op_sel_hi:[0,1,1]
	v_pk_fma_f32 v[14:15], v[88:89], v[46:47], v[14:15] op_sel_hi:[0,1,1]
	v_pk_fma_f32 v[16:17], v[90:91], v[46:47], v[16:17] op_sel_hi:[0,1,1]
	v_pk_fma_f32 v[18:19], v[92:93], v[46:47], v[18:19] op_sel_hi:[0,1,1]
	v_pk_fma_f32 v[20:21], v[94:95], v[46:47], v[20:21] op_sel_hi:[0,1,1]
	global_store_dword v154, v54, s[14:15] offset:-4096
	s_waitcnt vmcnt(8)
	v_lshlrev_b32_e32 v116, 16, v108
	v_lshlrev_b32_e32 v117, 16, v109
	v_and_b32_e32 v118, s17, v108
	v_and_b32_e32 v119, s17, v109
	v_lshlrev_b32_e32 v120, 16, v110
	v_and_b32_e32 v121, s17, v110
	v_lshlrev_b32_e32 v122, 16, v111
	v_and_b32_e32 v123, s17, v111
	v_lshlrev_b32_e32 v124, 16, v112
	v_and_b32_e32 v125, s17, v112
	ds_write_b128 v28, v[116:119]
	ds_write_b64 v29, v[120:121]
	ds_write_b64 v30, v[122:123]
	ds_write_b64 v30, v[124:125] offset:128
	ds_write_b32 v31, v113
	s_mov_b32 s0, s18
	s_mov_b32 s18, s19
	s_mov_b32 s19, s20
	s_mov_b32 s20, s0
	v_mov_b32_e32 v22, v25
	v_mov_b32_e32 v23, v26
	v_mov_b32_e32 v24, v27
	v_add_u32_e32 v25, s19, v2
	v_add_u32_e32 v26, s19, v3
	v_mov_b32_e32 v27, s19
	v_add_u32_e32 v28, s20, v32
	v_add_u32_e32 v29, s20, v33
	v_add_u32_e32 v30, s20, v34
	v_add_u32_e32 v31, s20, v35
	s_add_i32 s16, s16, 8
	s_waitcnt lgkmcnt(0)
	s_barrier
	s_cmpk_lt_u32 s16, 0x800
	s_cbranch_scc1 .Lgd2_loop
	s_setprio 0
	s_lshr_b32 s2, s27, 4
	s_lshl_b32 s4, s2, 16
	s_add_u32 s4, s4, 0x4080000
	s_add_u32 s0, s24, s4
	s_addc_u32 s1, s25, 0
	v_pk_mul_f32 v[108:109], v[6:7], v[50:51] op_sel:[0,1] op_sel_hi:[1,1]
	global_store_dwordx2 v153, v[108:109], s[0:1] offset:0
	v_pk_mul_f32 v[110:111], v[8:9], v[50:51] op_sel:[0,1] op_sel_hi:[1,1]
	global_store_dwordx2 v153, v[110:111], s[0:1] offset:512
	v_pk_mul_f32 v[108:109], v[10:11], v[50:51] op_sel:[0,1] op_sel_hi:[1,1]
	global_store_dwordx2 v153, v[108:109], s[0:1] offset:1024
	v_pk_mul_f32 v[110:111], v[12:13], v[50:51] op_sel:[0,1] op_sel_hi:[1,1]
	global_store_dwordx2 v153, v[110:111], s[0:1] offset:1536
	v_pk_mul_f32 v[108:109], v[14:15], v[50:51] op_sel:[0,1] op_sel_hi:[1,1]
	global_store_dwordx2 v153, v[108:109], s[0:1] offset:2048
	v_pk_mul_f32 v[110:111], v[16:17], v[50:51] op_sel:[0,1] op_sel_hi:[1,1]
	global_store_dwordx2 v153, v[110:111], s[0:1] offset:2560
	v_pk_mul_f32 v[108:109], v[18:19], v[50:51] op_sel:[0,1] op_sel_hi:[1,1]
	global_store_dwordx2 v153, v[108:109], s[0:1] offset:3072
	v_pk_mul_f32 v[110:111], v[20:21], v[50:51] op_sel:[0,1] op_sel_hi:[1,1]
	global_store_dwordx2 v153, v[110:111], s[0:1] offset:3584
	s_add_i32 s27, s27, s28
	s_waitcnt vmcnt(0)
	s_cmpk_lt_i32 s27, 0x400
	s_cbranch_scc1 .Lgd2_item
	s_branch .LBB0_232
.Lgd2_rare0:
	v_pk_mul_f32 v[6:7], v[6:7], v[50:51] op_sel:[0,0] op_sel_hi:[1,0]
	v_pk_mul_f32 v[8:9], v[8:9], v[50:51] op_sel:[0,0] op_sel_hi:[1,0]
	v_pk_mul_f32 v[10:11], v[10:11], v[50:51] op_sel:[0,0] op_sel_hi:[1,0]
	v_pk_mul_f32 v[12:13], v[12:13], v[50:51] op_sel:[0,0] op_sel_hi:[1,0]
	v_pk_mul_f32 v[14:15], v[14:15], v[50:51] op_sel:[0,0] op_sel_hi:[1,0]
	v_pk_mul_f32 v[16:17], v[16:17], v[50:51] op_sel:[0,0] op_sel_hi:[1,0]
	v_pk_mul_f32 v[18:19], v[18:19], v[50:51] op_sel:[0,0] op_sel_hi:[1,0]
	v_pk_mul_f32 v[20:21], v[20:21], v[50:51] op_sel:[0,0] op_sel_hi:[1,0]
	v_mov_b32_e32 v50, 1.0
	v_mov_b32_e32 v52, 1.0
	s_branch .Lgd2_back0
.Lgd2_rare1:
	v_pk_mul_f32 v[6:7], v[6:7], v[50:51] op_sel:[0,1] op_sel_hi:[1,1]
	v_pk_mul_f32 v[8:9], v[8:9], v[50:51] op_sel:[0,1] op_sel_hi:[1,1]
	v_pk_mul_f32 v[10:11], v[10:11], v[50:51] op_sel:[0,1] op_sel_hi:[1,1]
	v_pk_mul_f32 v[12:13], v[12:13], v[50:51] op_sel:[0,1] op_sel_hi:[1,1]
	v_pk_mul_f32 v[14:15], v[14:15], v[50:51] op_sel:[0,1] op_sel_hi:[1,1]
	v_pk_mul_f32 v[16:17], v[16:17], v[50:51] op_sel:[0,1] op_sel_hi:[1,1]
	v_pk_mul_f32 v[18:19], v[18:19], v[50:51] op_sel:[0,1] op_sel_hi:[1,1]
	v_pk_mul_f32 v[20:21], v[20:21], v[50:51] op_sel:[0,1] op_sel_hi:[1,1]
	v_mov_b32_e32 v51, 1.0
	v_mov_b32_e32 v52, 1.0
	s_branch .Lgd2_back1
